# v27 + E6X: FF1 epilogue rewritten so every store instruction writes eight full 128-byte lines (row_ror:8 half exchange)
# speedup vs baseline: 1.0133x; 1.0088x over previous
; __device__ __forceinline__ u32x4 pack8(const f32x4 a, const f32x4 b) { u32x4 w; w.x = cvt_pk_bf16(a[0], a[1]); w.y = cvt_pk_bf16(a[2], a[3]); w.z = cvt_pk_bf16(b[0], b[1]); w.w = cvt_pk_bf16(b[2], b[3]); return w; }
;     __device__ __forceinline__ void operator()(const f32x4 (&acc)[2][2][4][2], const Unit& u, int wr, int wc, int fr, int fq) const {
;         const int rowb = u.pm * BM + wr * 64 + fr; const int col0 = u.pn * BM + wc * 64 + 8 * fq;
; #pragma unroll
;         for (int ai = 0; ai < 2; ++ai)
; #pragma unroll
;             for (int m = 0; m < 4; ++m) { bf16_t* rp = H + (size_t)(rowb + ai * HALF + m * 16) * 4096 + col0;
; #pragma unroll
;                 for (int bj = 0; bj < 2; ++bj) { f32x4 v0 = acc[ai][bj][m][0], v1 = acc[ai][bj][m][1];
; #pragma unroll
;                     for (int e = 0; e < 4; ++e) { const float a = fmaxf(v0[e], 0.f), b = fmaxf(v1[e], 0.f); v0[e] = a * a; v1[e] = b * b; }
;                     __builtin_nontemporal_store(pack8(v0, v1), (u32x4*)(rp + bj * 32)); } }
.LBB0_1343:
	v_lshl_add_u32 v162, s30, 8, v158
	v_and_b32_e32 v172, 8, v212
	v_and_b32_e32 v162, 0xfffffff7, v162
	v_cmp_eq_u32_e64 s[98:99], 0, v172
	v_ashrrev_i32_e32 v163, 31, v162
	v_lshl_or_b32 v156, s28, 8, v160
	v_lshl_or_b32 v156, v172, 2, v156
	v_lshlrev_b64 v[164:165], 13, v[162:163]
	v_ashrrev_i32_e32 v157, 31, v156
	v_lshl_add_u64 v[164:165], s[4:5], 0, v[164:165]
	v_lshlrev_b64 v[166:167], 1, v[156:157]
	v_lshl_add_u64 v[156:157], v[164:165], 0, v[166:167]
	v_max_f32_e32 v142, 0, v142
	v_max_f32_e32 v143, 0, v143
	v_max_f32_e32 v144, 0, v144
	v_max_f32_e32 v145, 0, v145
	v_max_f32_e32 v138, 0, v138
	v_max_f32_e32 v139, 0, v139
	v_max_f32_e32 v140, 0, v140
	v_max_f32_e32 v141, 0, v141
	v_max_f32_e32 v134, 0, v134
	v_max_f32_e32 v135, 0, v135
	v_max_f32_e32 v136, 0, v136
	v_max_f32_e32 v137, 0, v137
	v_max_f32_e32 v130, 0, v130
	v_max_f32_e32 v131, 0, v131
	v_max_f32_e32 v132, 0, v132
	v_max_f32_e32 v133, 0, v133
	v_pk_mul_f32 v[142:143], v[142:143], v[142:143]
	v_pk_mul_f32 v[144:145], v[144:145], v[144:145]
	v_pk_mul_f32 v[138:139], v[138:139], v[138:139]
	v_pk_mul_f32 v[140:141], v[140:141], v[140:141]
	v_pk_mul_f32 v[134:135], v[134:135], v[134:135]
	v_pk_mul_f32 v[136:137], v[136:137], v[136:137]
	v_pk_mul_f32 v[130:131], v[130:131], v[130:131]
	v_pk_mul_f32 v[132:133], v[132:133], v[132:133]
	v_cvt_pk_bf16_f32 v142, v142, v143
	v_cvt_pk_bf16_f32 v143, v144, v145
	v_cvt_pk_bf16_f32 v144, v138, v139
	v_cvt_pk_bf16_f32 v145, v140, v141
	v_cvt_pk_bf16_f32 v134, v134, v135
	v_cvt_pk_bf16_f32 v135, v136, v137
	v_cvt_pk_bf16_f32 v136, v130, v131
	v_cvt_pk_bf16_f32 v137, v132, v133
	v_cndmask_b32_e64 v138, v142, v134, s[98:99]
	v_cndmask_b32_e64 v139, v143, v135, s[98:99]
	v_cndmask_b32_e64 v140, v144, v136, s[98:99]
	v_cndmask_b32_e64 v141, v145, v137, s[98:99]
	v_mov_b32_dpp v130, v138 row_ror:8 row_mask:0xf bank_mask:0xf
	v_mov_b32_dpp v131, v139 row_ror:8 row_mask:0xf bank_mask:0xf
	v_mov_b32_dpp v132, v140 row_ror:8 row_mask:0xf bank_mask:0xf
	v_mov_b32_dpp v133, v141 row_ror:8 row_mask:0xf bank_mask:0xf
	v_add_co_u32_e32 v170, vcc, 0x10000, v156
	v_addc_co_u32_e32 v171, vcc, 0, v157, vcc
	v_cndmask_b32_e64 v142, v130, v142, s[98:99]
	v_cndmask_b32_e64 v143, v131, v143, s[98:99]
	v_cndmask_b32_e64 v144, v132, v144, s[98:99]
	v_cndmask_b32_e64 v145, v133, v145, s[98:99]
	v_cndmask_b32_e64 v134, v134, v130, s[98:99]
	v_cndmask_b32_e64 v135, v135, v131, s[98:99]
	v_cndmask_b32_e64 v136, v136, v132, s[98:99]
	v_cndmask_b32_e64 v137, v137, v133, s[98:99]
	global_store_dwordx4 v[156:157], v[142:145], off nt
	global_store_dwordx4 v[170:171], v[134:137], off nt
	v_max_f32_e32 v110, 0, v110
	v_max_f32_e32 v111, 0, v111
	v_max_f32_e32 v112, 0, v112
	v_max_f32_e32 v113, 0, v113
	v_max_f32_e32 v106, 0, v106
	v_max_f32_e32 v107, 0, v107
	v_max_f32_e32 v108, 0, v108
	v_max_f32_e32 v109, 0, v109
	v_max_f32_e32 v102, 0, v102
	v_max_f32_e32 v103, 0, v103
	v_max_f32_e32 v104, 0, v104
	v_max_f32_e32 v105, 0, v105
	v_max_f32_e32 v98, 0, v98
	v_max_f32_e32 v99, 0, v99
	v_max_f32_e32 v100, 0, v100
	v_max_f32_e32 v101, 0, v101
	v_pk_mul_f32 v[110:111], v[110:111], v[110:111]
	v_pk_mul_f32 v[112:113], v[112:113], v[112:113]
	v_pk_mul_f32 v[106:107], v[106:107], v[106:107]
	v_pk_mul_f32 v[108:109], v[108:109], v[108:109]
	v_pk_mul_f32 v[102:103], v[102:103], v[102:103]
	v_pk_mul_f32 v[104:105], v[104:105], v[104:105]
	v_pk_mul_f32 v[98:99], v[98:99], v[98:99]
	v_pk_mul_f32 v[100:101], v[100:101], v[100:101]
	v_cvt_pk_bf16_f32 v110, v110, v111
	v_cvt_pk_bf16_f32 v111, v112, v113
	v_cvt_pk_bf16_f32 v112, v106, v107
	v_cvt_pk_bf16_f32 v113, v108, v109
	v_cvt_pk_bf16_f32 v102, v102, v103
	v_cvt_pk_bf16_f32 v103, v104, v105
	v_cvt_pk_bf16_f32 v104, v98, v99
	v_cvt_pk_bf16_f32 v105, v100, v101
	v_add_co_u32_e32 v174, vcc, 0x20000, v156
	v_addc_co_u32_e32 v175, vcc, 0, v157, vcc
	v_cndmask_b32_e64 v106, v110, v102, s[98:99]
	v_cndmask_b32_e64 v107, v111, v103, s[98:99]
	v_cndmask_b32_e64 v108, v112, v104, s[98:99]
	v_cndmask_b32_e64 v109, v113, v105, s[98:99]
	v_mov_b32_dpp v98, v106 row_ror:8 row_mask:0xf bank_mask:0xf
	v_mov_b32_dpp v99, v107 row_ror:8 row_mask:0xf bank_mask:0xf
	v_mov_b32_dpp v100, v108 row_ror:8 row_mask:0xf bank_mask:0xf
	v_mov_b32_dpp v101, v109 row_ror:8 row_mask:0xf bank_mask:0xf
	v_add_co_u32_e32 v176, vcc, 0x30000, v156
	v_addc_co_u32_e32 v177, vcc, 0, v157, vcc
	v_cndmask_b32_e64 v110, v98, v110, s[98:99]
	v_cndmask_b32_e64 v111, v99, v111, s[98:99]
	v_cndmask_b32_e64 v112, v100, v112, s[98:99]
	v_cndmask_b32_e64 v113, v101, v113, s[98:99]
	v_cndmask_b32_e64 v102, v102, v98, s[98:99]
	v_cndmask_b32_e64 v103, v103, v99, s[98:99]
	v_cndmask_b32_e64 v104, v104, v100, s[98:99]
	v_cndmask_b32_e64 v105, v105, v101, s[98:99]
	global_store_dwordx4 v[174:175], v[110:113], off nt
	global_store_dwordx4 v[176:177], v[102:105], off nt
	v_max_f32_e32 v94, 0, v94
	v_max_f32_e32 v95, 0, v95
	v_max_f32_e32 v96, 0, v96
	v_max_f32_e32 v97, 0, v97
	v_max_f32_e32 v90, 0, v90
	v_max_f32_e32 v91, 0, v91
	v_max_f32_e32 v92, 0, v92
	v_max_f32_e32 v93, 0, v93
	v_max_f32_e32 v86, 0, v86
	v_max_f32_e32 v87, 0, v87
	v_max_f32_e32 v88, 0, v88
	v_max_f32_e32 v89, 0, v89
	v_max_f32_e32 v82, 0, v82
	v_max_f32_e32 v83, 0, v83
	v_max_f32_e32 v84, 0, v84
	v_max_f32_e32 v85, 0, v85
	v_pk_mul_f32 v[94:95], v[94:95], v[94:95]
	v_pk_mul_f32 v[96:97], v[96:97], v[96:97]
	v_pk_mul_f32 v[90:91], v[90:91], v[90:91]
	v_pk_mul_f32 v[92:93], v[92:93], v[92:93]
	v_pk_mul_f32 v[86:87], v[86:87], v[86:87]
	v_pk_mul_f32 v[88:89], v[88:89], v[88:89]
	v_pk_mul_f32 v[82:83], v[82:83], v[82:83]
	v_pk_mul_f32 v[84:85], v[84:85], v[84:85]
	v_cvt_pk_bf16_f32 v94, v94, v95
; __device__ __forceinline__ u32x4 pack8(const f32x4 a, const f32x4 b) { u32x4 w; w.x = cvt_pk_bf16(a[0], a[1]); w.y = cvt_pk_bf16(a[2], a[3]); w.z = cvt_pk_bf16(b[0], b[1]); w.w = cvt_pk_bf16(b[2], b[3]); return w; }
;     __device__ __forceinline__ void operator()(const f32x4 (&acc)[2][2][4][2], const Unit& u, int wr, int wc, int fr, int fq) const {
;         const int rowb = u.pm * BM + wr * 64 + fr; const int col0 = u.pn * BM + wc * 64 + 8 * fq;
; #pragma unroll
;         for (int ai = 0; ai < 2; ++ai)
; #pragma unroll
;             for (int m = 0; m < 4; ++m) { bf16_t* rp = H + (size_t)(rowb + ai * HALF + m * 16) * 4096 + col0;
; #pragma unroll
;                 for (int bj = 0; bj < 2; ++bj) { f32x4 v0 = acc[ai][bj][m][0], v1 = acc[ai][bj][m][1];
; #pragma unroll
;                     for (int e = 0; e < 4; ++e) { const float a = fmaxf(v0[e], 0.f), b = fmaxf(v1[e], 0.f); v0[e] = a * a; v1[e] = b * b; }
;                     __builtin_nontemporal_store(pack8(v0, v1), (u32x4*)(rp + bj * 32)); } }
	v_cvt_pk_bf16_f32 v95, v96, v97
	v_cvt_pk_bf16_f32 v96, v90, v91
	v_cvt_pk_bf16_f32 v97, v92, v93
	v_cvt_pk_bf16_f32 v86, v86, v87
	v_cvt_pk_bf16_f32 v87, v88, v89
	v_cvt_pk_bf16_f32 v88, v82, v83
	v_cvt_pk_bf16_f32 v89, v84, v85
	v_add_co_u32_e32 v168, vcc, 0x40000, v156
	v_addc_co_u32_e32 v169, vcc, 0, v157, vcc
	v_cndmask_b32_e64 v90, v94, v86, s[98:99]
	v_cndmask_b32_e64 v91, v95, v87, s[98:99]
	v_cndmask_b32_e64 v92, v96, v88, s[98:99]
	v_cndmask_b32_e64 v93, v97, v89, s[98:99]
	v_mov_b32_dpp v82, v90 row_ror:8 row_mask:0xf bank_mask:0xf
	v_mov_b32_dpp v83, v91 row_ror:8 row_mask:0xf bank_mask:0xf
	v_mov_b32_dpp v84, v92 row_ror:8 row_mask:0xf bank_mask:0xf
	v_mov_b32_dpp v85, v93 row_ror:8 row_mask:0xf bank_mask:0xf
	v_add_co_u32_e32 v170, vcc, 0x50000, v156
	v_addc_co_u32_e32 v171, vcc, 0, v157, vcc
	v_cndmask_b32_e64 v94, v82, v94, s[98:99]
	v_cndmask_b32_e64 v95, v83, v95, s[98:99]
	v_cndmask_b32_e64 v96, v84, v96, s[98:99]
	v_cndmask_b32_e64 v97, v85, v97, s[98:99]
	v_cndmask_b32_e64 v86, v86, v82, s[98:99]
	v_cndmask_b32_e64 v87, v87, v83, s[98:99]
	v_cndmask_b32_e64 v88, v88, v84, s[98:99]
	v_cndmask_b32_e64 v89, v89, v85, s[98:99]
	global_store_dwordx4 v[168:169], v[94:97], off nt
	global_store_dwordx4 v[170:171], v[86:89], off nt
	v_max_f32_e32 v78, 0, v78
	v_max_f32_e32 v79, 0, v79
	v_max_f32_e32 v80, 0, v80
	v_max_f32_e32 v81, 0, v81
	v_max_f32_e32 v74, 0, v74
	v_max_f32_e32 v75, 0, v75
	v_max_f32_e32 v76, 0, v76
	v_max_f32_e32 v77, 0, v77
	v_max_f32_e32 v70, 0, v70
	v_max_f32_e32 v71, 0, v71
	v_max_f32_e32 v72, 0, v72
	v_max_f32_e32 v73, 0, v73
	v_max_f32_e32 v66, 0, v66
	v_max_f32_e32 v67, 0, v67
	v_max_f32_e32 v68, 0, v68
	v_max_f32_e32 v69, 0, v69
	v_pk_mul_f32 v[78:79], v[78:79], v[78:79]
	v_pk_mul_f32 v[80:81], v[80:81], v[80:81]
	v_pk_mul_f32 v[74:75], v[74:75], v[74:75]
	v_pk_mul_f32 v[76:77], v[76:77], v[76:77]
	v_pk_mul_f32 v[70:71], v[70:71], v[70:71]
	v_pk_mul_f32 v[72:73], v[72:73], v[72:73]
	v_pk_mul_f32 v[66:67], v[66:67], v[66:67]
	v_pk_mul_f32 v[68:69], v[68:69], v[68:69]
	v_cvt_pk_bf16_f32 v78, v78, v79
	v_cvt_pk_bf16_f32 v79, v80, v81
	v_cvt_pk_bf16_f32 v80, v74, v75
	v_cvt_pk_bf16_f32 v81, v76, v77
	v_cvt_pk_bf16_f32 v70, v70, v71
	v_cvt_pk_bf16_f32 v71, v72, v73
	v_cvt_pk_bf16_f32 v72, v66, v67
	v_cvt_pk_bf16_f32 v73, v68, v69
	v_add_co_u32_e32 v174, vcc, 0x60000, v156
	v_addc_co_u32_e32 v175, vcc, 0, v157, vcc
	v_cndmask_b32_e64 v74, v78, v70, s[98:99]
	v_cndmask_b32_e64 v75, v79, v71, s[98:99]
	v_cndmask_b32_e64 v76, v80, v72, s[98:99]
	v_cndmask_b32_e64 v77, v81, v73, s[98:99]
	v_mov_b32_dpp v66, v74 row_ror:8 row_mask:0xf bank_mask:0xf
	v_mov_b32_dpp v67, v75 row_ror:8 row_mask:0xf bank_mask:0xf
	v_mov_b32_dpp v68, v76 row_ror:8 row_mask:0xf bank_mask:0xf
	v_mov_b32_dpp v69, v77 row_ror:8 row_mask:0xf bank_mask:0xf
	v_add_co_u32_e32 v176, vcc, 0x70000, v156
	v_addc_co_u32_e32 v177, vcc, 0, v157, vcc
	v_cndmask_b32_e64 v78, v66, v78, s[98:99]
	v_cndmask_b32_e64 v79, v67, v79, s[98:99]
	v_cndmask_b32_e64 v80, v68, v80, s[98:99]
	v_cndmask_b32_e64 v81, v69, v81, s[98:99]
	v_cndmask_b32_e64 v70, v70, v66, s[98:99]
	v_cndmask_b32_e64 v71, v71, v67, s[98:99]
	v_cndmask_b32_e64 v72, v72, v68, s[98:99]
	v_cndmask_b32_e64 v73, v73, v69, s[98:99]
	global_store_dwordx4 v[174:175], v[78:81], off nt
	global_store_dwordx4 v[176:177], v[70:73], off nt
	v_max_f32_e32 v62, 0, v62
	v_max_f32_e32 v63, 0, v63
	v_max_f32_e32 v64, 0, v64
	v_max_f32_e32 v65, 0, v65
	v_max_f32_e32 v58, 0, v58
	v_max_f32_e32 v59, 0, v59
	v_max_f32_e32 v60, 0, v60
	v_max_f32_e32 v61, 0, v61
	v_max_f32_e32 v54, 0, v54
	v_max_f32_e32 v55, 0, v55
	v_max_f32_e32 v56, 0, v56
	v_max_f32_e32 v57, 0, v57
	v_max_f32_e32 v50, 0, v50
	v_max_f32_e32 v51, 0, v51
	v_max_f32_e32 v52, 0, v52
	v_max_f32_e32 v53, 0, v53
	v_pk_mul_f32 v[62:63], v[62:63], v[62:63]
	v_pk_mul_f32 v[64:65], v[64:65], v[64:65]
	v_pk_mul_f32 v[58:59], v[58:59], v[58:59]
	v_pk_mul_f32 v[60:61], v[60:61], v[60:61]
	v_pk_mul_f32 v[54:55], v[54:55], v[54:55]
	v_pk_mul_f32 v[56:57], v[56:57], v[56:57]
	v_pk_mul_f32 v[50:51], v[50:51], v[50:51]
	v_pk_mul_f32 v[52:53], v[52:53], v[52:53]
	v_cvt_pk_bf16_f32 v62, v62, v63
	v_cvt_pk_bf16_f32 v63, v64, v65
	v_cvt_pk_bf16_f32 v64, v58, v59
	v_cvt_pk_bf16_f32 v65, v60, v61
	v_cvt_pk_bf16_f32 v54, v54, v55
	v_cvt_pk_bf16_f32 v55, v56, v57
	v_cvt_pk_bf16_f32 v56, v50, v51
	v_cvt_pk_bf16_f32 v57, v52, v53
	v_add_co_u32_e32 v168, vcc, 0x100000, v156
	v_addc_co_u32_e32 v169, vcc, 0, v157, vcc
	v_cndmask_b32_e64 v58, v62, v54, s[98:99]
	v_cndmask_b32_e64 v59, v63, v55, s[98:99]
	v_cndmask_b32_e64 v60, v64, v56, s[98:99]
	v_cndmask_b32_e64 v61, v65, v57, s[98:99]
	v_mov_b32_dpp v50, v58 row_ror:8 row_mask:0xf bank_mask:0xf
	v_mov_b32_dpp v51, v59 row_ror:8 row_mask:0xf bank_mask:0xf
	v_mov_b32_dpp v52, v60 row_ror:8 row_mask:0xf bank_mask:0xf
	v_mov_b32_dpp v53, v61 row_ror:8 row_mask:0xf bank_mask:0xf
	v_add_co_u32_e32 v170, vcc, 0x110000, v156
	v_addc_co_u32_e32 v171, vcc, 0, v157, vcc
	v_cndmask_b32_e64 v62, v50, v62, s[98:99]
	v_cndmask_b32_e64 v63, v51, v63, s[98:99]
	v_cndmask_b32_e64 v64, v52, v64, s[98:99]
	v_cndmask_b32_e64 v65, v53, v65, s[98:99]
	v_cndmask_b32_e64 v54, v54, v50, s[98:99]
	v_cndmask_b32_e64 v55, v55, v51, s[98:99]
	v_cndmask_b32_e64 v56, v56, v52, s[98:99]
	v_cndmask_b32_e64 v57, v57, v53, s[98:99]
	global_store_dwordx4 v[168:169], v[62:65], off nt
	global_store_dwordx4 v[170:171], v[54:57], off nt
	v_max_f32_e32 v46, 0, v46
	v_max_f32_e32 v47, 0, v47
	v_max_f32_e32 v48, 0, v48
	v_max_f32_e32 v49, 0, v49
	v_max_f32_e32 v42, 0, v42
	v_max_f32_e32 v43, 0, v43
	v_max_f32_e32 v44, 0, v44
	v_max_f32_e32 v45, 0, v45
; __device__ __forceinline__ u32x4 pack8(const f32x4 a, const f32x4 b) { u32x4 w; w.x = cvt_pk_bf16(a[0], a[1]); w.y = cvt_pk_bf16(a[2], a[3]); w.z = cvt_pk_bf16(b[0], b[1]); w.w = cvt_pk_bf16(b[2], b[3]); return w; }
;     __device__ __forceinline__ void operator()(const f32x4 (&acc)[2][2][4][2], const Unit& u, int wr, int wc, int fr, int fq) const {
;         const int rowb = u.pm * BM + wr * 64 + fr; const int col0 = u.pn * BM + wc * 64 + 8 * fq;
; #pragma unroll
;         for (int ai = 0; ai < 2; ++ai)
; #pragma unroll
;             for (int m = 0; m < 4; ++m) { bf16_t* rp = H + (size_t)(rowb + ai * HALF + m * 16) * 4096 + col0;
; #pragma unroll
;                 for (int bj = 0; bj < 2; ++bj) { f32x4 v0 = acc[ai][bj][m][0], v1 = acc[ai][bj][m][1];
; #pragma unroll
;                     for (int e = 0; e < 4; ++e) { const float a = fmaxf(v0[e], 0.f), b = fmaxf(v1[e], 0.f); v0[e] = a * a; v1[e] = b * b; }
;                     __builtin_nontemporal_store(pack8(v0, v1), (u32x4*)(rp + bj * 32)); } }
	v_max_f32_e32 v38, 0, v38
	v_max_f32_e32 v39, 0, v39
	v_max_f32_e32 v40, 0, v40
	v_max_f32_e32 v41, 0, v41
	v_max_f32_e32 v34, 0, v34
	v_max_f32_e32 v35, 0, v35
	v_max_f32_e32 v36, 0, v36
	v_max_f32_e32 v37, 0, v37
	v_pk_mul_f32 v[46:47], v[46:47], v[46:47]
	v_pk_mul_f32 v[48:49], v[48:49], v[48:49]
	v_pk_mul_f32 v[42:43], v[42:43], v[42:43]
	v_pk_mul_f32 v[44:45], v[44:45], v[44:45]
	v_pk_mul_f32 v[38:39], v[38:39], v[38:39]
	v_pk_mul_f32 v[40:41], v[40:41], v[40:41]
	v_pk_mul_f32 v[34:35], v[34:35], v[34:35]
	v_pk_mul_f32 v[36:37], v[36:37], v[36:37]
	v_cvt_pk_bf16_f32 v46, v46, v47
	v_cvt_pk_bf16_f32 v47, v48, v49
	v_cvt_pk_bf16_f32 v48, v42, v43
	v_cvt_pk_bf16_f32 v49, v44, v45
	v_cvt_pk_bf16_f32 v38, v38, v39
	v_cvt_pk_bf16_f32 v39, v40, v41
	v_cvt_pk_bf16_f32 v40, v34, v35
	v_cvt_pk_bf16_f32 v41, v36, v37
	v_add_co_u32_e32 v174, vcc, 0x120000, v156
	v_addc_co_u32_e32 v175, vcc, 0, v157, vcc
	v_cndmask_b32_e64 v42, v46, v38, s[98:99]
	v_cndmask_b32_e64 v43, v47, v39, s[98:99]
	v_cndmask_b32_e64 v44, v48, v40, s[98:99]
	v_cndmask_b32_e64 v45, v49, v41, s[98:99]
	v_mov_b32_dpp v34, v42 row_ror:8 row_mask:0xf bank_mask:0xf
	v_mov_b32_dpp v35, v43 row_ror:8 row_mask:0xf bank_mask:0xf
	v_mov_b32_dpp v36, v44 row_ror:8 row_mask:0xf bank_mask:0xf
	v_mov_b32_dpp v37, v45 row_ror:8 row_mask:0xf bank_mask:0xf
	v_add_co_u32_e32 v176, vcc, 0x130000, v156
	v_addc_co_u32_e32 v177, vcc, 0, v157, vcc
	v_cndmask_b32_e64 v46, v34, v46, s[98:99]
	v_cndmask_b32_e64 v47, v35, v47, s[98:99]
	v_cndmask_b32_e64 v48, v36, v48, s[98:99]
	v_cndmask_b32_e64 v49, v37, v49, s[98:99]
	v_cndmask_b32_e64 v38, v38, v34, s[98:99]
	v_cndmask_b32_e64 v39, v39, v35, s[98:99]
	v_cndmask_b32_e64 v40, v40, v36, s[98:99]
	v_cndmask_b32_e64 v41, v41, v37, s[98:99]
	global_store_dwordx4 v[174:175], v[46:49], off nt
	global_store_dwordx4 v[176:177], v[38:41], off nt
	v_max_f32_e32 v30, 0, v30
	v_max_f32_e32 v31, 0, v31
	v_max_f32_e32 v32, 0, v32
	v_max_f32_e32 v33, 0, v33
	v_max_f32_e32 v26, 0, v26
	v_max_f32_e32 v27, 0, v27
	v_max_f32_e32 v28, 0, v28
	v_max_f32_e32 v29, 0, v29
	v_max_f32_e32 v22, 0, v22
	v_max_f32_e32 v23, 0, v23
	v_max_f32_e32 v24, 0, v24
	v_max_f32_e32 v25, 0, v25
	v_max_f32_e32 v18, 0, v18
	v_max_f32_e32 v19, 0, v19
	v_max_f32_e32 v20, 0, v20
	v_max_f32_e32 v21, 0, v21
	v_pk_mul_f32 v[30:31], v[30:31], v[30:31]
	v_pk_mul_f32 v[32:33], v[32:33], v[32:33]
	v_pk_mul_f32 v[26:27], v[26:27], v[26:27]
	v_pk_mul_f32 v[28:29], v[28:29], v[28:29]
	v_pk_mul_f32 v[22:23], v[22:23], v[22:23]
	v_pk_mul_f32 v[24:25], v[24:25], v[24:25]
	v_pk_mul_f32 v[18:19], v[18:19], v[18:19]
	v_pk_mul_f32 v[20:21], v[20:21], v[20:21]
	v_cvt_pk_bf16_f32 v30, v30, v31
	v_cvt_pk_bf16_f32 v31, v32, v33
	v_cvt_pk_bf16_f32 v32, v26, v27
	v_cvt_pk_bf16_f32 v33, v28, v29
	v_cvt_pk_bf16_f32 v22, v22, v23
	v_cvt_pk_bf16_f32 v23, v24, v25
	v_cvt_pk_bf16_f32 v24, v18, v19
	v_cvt_pk_bf16_f32 v25, v20, v21
	v_add_co_u32_e32 v168, vcc, 0x140000, v156
	v_addc_co_u32_e32 v169, vcc, 0, v157, vcc
	v_cndmask_b32_e64 v26, v30, v22, s[98:99]
	v_cndmask_b32_e64 v27, v31, v23, s[98:99]
	v_cndmask_b32_e64 v28, v32, v24, s[98:99]
	v_cndmask_b32_e64 v29, v33, v25, s[98:99]
	v_mov_b32_dpp v18, v26 row_ror:8 row_mask:0xf bank_mask:0xf
	v_mov_b32_dpp v19, v27 row_ror:8 row_mask:0xf bank_mask:0xf
	v_mov_b32_dpp v20, v28 row_ror:8 row_mask:0xf bank_mask:0xf
	v_mov_b32_dpp v21, v29 row_ror:8 row_mask:0xf bank_mask:0xf
	v_add_co_u32_e32 v170, vcc, 0x150000, v156
	v_addc_co_u32_e32 v171, vcc, 0, v157, vcc
	v_cndmask_b32_e64 v30, v18, v30, s[98:99]
	v_cndmask_b32_e64 v31, v19, v31, s[98:99]
	v_cndmask_b32_e64 v32, v20, v32, s[98:99]
	v_cndmask_b32_e64 v33, v21, v33, s[98:99]
	v_cndmask_b32_e64 v22, v22, v18, s[98:99]
	v_cndmask_b32_e64 v23, v23, v19, s[98:99]
	v_cndmask_b32_e64 v24, v24, v20, s[98:99]
	v_cndmask_b32_e64 v25, v25, v21, s[98:99]
	global_store_dwordx4 v[168:169], v[30:33], off nt
	global_store_dwordx4 v[170:171], v[22:25], off nt
	v_max_f32_e32 v14, 0, v14
	v_max_f32_e32 v15, 0, v15
	v_max_f32_e32 v16, 0, v16
	v_max_f32_e32 v17, 0, v17
	v_max_f32_e32 v10, 0, v10
	v_max_f32_e32 v11, 0, v11
	v_max_f32_e32 v12, 0, v12
	v_max_f32_e32 v13, 0, v13
	v_max_f32_e32 v6, 0, v6
	v_max_f32_e32 v7, 0, v7
	v_max_f32_e32 v8, 0, v8
	v_max_f32_e32 v9, 0, v9
	v_max_f32_e32 v2, 0, v2
	v_max_f32_e32 v3, 0, v3
	v_max_f32_e32 v4, 0, v4
	v_max_f32_e32 v5, 0, v5
	v_pk_mul_f32 v[14:15], v[14:15], v[14:15]
	v_pk_mul_f32 v[16:17], v[16:17], v[16:17]
	v_pk_mul_f32 v[10:11], v[10:11], v[10:11]
	v_pk_mul_f32 v[12:13], v[12:13], v[12:13]
	v_pk_mul_f32 v[6:7], v[6:7], v[6:7]
	v_pk_mul_f32 v[8:9], v[8:9], v[8:9]
	v_pk_mul_f32 v[2:3], v[2:3], v[2:3]
	v_pk_mul_f32 v[4:5], v[4:5], v[4:5]
	v_cvt_pk_bf16_f32 v14, v14, v15
	v_cvt_pk_bf16_f32 v15, v16, v17
	v_cvt_pk_bf16_f32 v16, v10, v11
	v_cvt_pk_bf16_f32 v17, v12, v13
	v_cvt_pk_bf16_f32 v6, v6, v7
	v_cvt_pk_bf16_f32 v7, v8, v9
	v_cvt_pk_bf16_f32 v8, v2, v3
	v_cvt_pk_bf16_f32 v9, v4, v5
	v_add_co_u32_e32 v174, vcc, 0x160000, v156
	v_addc_co_u32_e32 v175, vcc, 0, v157, vcc
	v_cndmask_b32_e64 v10, v14, v6, s[98:99]
	v_cndmask_b32_e64 v11, v15, v7, s[98:99]
	v_cndmask_b32_e64 v12, v16, v8, s[98:99]
	v_cndmask_b32_e64 v13, v17, v9, s[98:99]
	v_mov_b32_dpp v2, v10 row_ror:8 row_mask:0xf bank_mask:0xf
	v_mov_b32_dpp v3, v11 row_ror:8 row_mask:0xf bank_mask:0xf
	v_mov_b32_dpp v4, v12 row_ror:8 row_mask:0xf bank_mask:0xf
	v_mov_b32_dpp v5, v13 row_ror:8 row_mask:0xf bank_mask:0xf
	v_add_co_u32_e32 v176, vcc, 0x170000, v156
	v_addc_co_u32_e32 v177, vcc, 0, v157, vcc
	v_cndmask_b32_e64 v14, v2, v14, s[98:99]
	v_cndmask_b32_e64 v15, v3, v15, s[98:99]
	v_cndmask_b32_e64 v16, v4, v16, s[98:99]
	v_cndmask_b32_e64 v17, v5, v17, s[98:99]
	v_cndmask_b32_e64 v6, v6, v2, s[98:99]
	v_cndmask_b32_e64 v7, v7, v3, s[98:99]
	v_cndmask_b32_e64 v8, v8, v4, s[98:99]
	v_cndmask_b32_e64 v9, v9, v5, s[98:99]
	global_store_dwordx4 v[174:175], v[14:17], off nt
	global_store_dwordx4 v[176:177], v[6:9], off nt
	s_andn2_b64 vcc, exec, s[0:1]
	s_mov_b64 s[0:1], -1
	s_cbranch_vccnz .LBB0_1336
	s_andn2_b64 vcc, exec, s[16:17]
	s_cbranch_vccnz .LBB0_1335
	s_barrier
	s_branch .LBB0_1335
